# v15: v14 + NSA br==2 item-head load prefetched in branch epilogue (LBB0_1215 round trip removed)
# speedup vs baseline: 1.1996x; 1.0013x over previous
.LBB0_1215:
	v_readlane_b32 s10, v254, 51
	v_readlane_b32 s11, v254, 52
	s_movk_i32 s3, 0x2000
	v_lshlrev_b32_e32 v6, 16, v146
	v_and_b32_e32 v7, 0xffff0000, v146
	v_lshlrev_b32_e32 v4, 16, v147
	v_and_b32_e32 v5, 0xffff0000, v147
	v_pk_mul_f32 v[6:7], v[8:9], v[6:7]
	v_pk_mul_f32 v[2:3], v[2:3], v[4:5]
	v_cvt_pk_bf16_f32 v4, v6, v7
	v_cvt_pk_bf16_f32 v5, v2, v3
	global_store_dwordx2 v[152:153], v[4:5], off offset:480

.LBB0_1307:
	v_lshl_add_u64 v[2:3], s[16:17], 2, v[154:155]
	global_load_dwordx2 v[80:81], v[152:153], off
	global_load_dwordx2 v[82:83], v[152:153], off offset:32
	global_load_dwordx2 v[84:85], v[152:153], off offset:64
	global_load_dwordx2 v[86:87], v[152:153], off offset:96
	global_load_dwordx2 v[88:89], v[152:153], off offset:128
	global_load_dwordx2 v[90:91], v[152:153], off offset:160
	global_load_dwordx2 v[92:93], v[152:153], off offset:192
	global_load_dwordx2 v[94:95], v[152:153], off offset:224
	global_load_dwordx2 v[96:97], v[152:153], off offset:256
	global_load_dwordx2 v[98:99], v[152:153], off offset:288
	global_load_dwordx2 v[100:101], v[152:153], off offset:320
	global_load_dwordx2 v[102:103], v[152:153], off offset:352
	global_load_dwordx2 v[104:105], v[152:153], off offset:384
	global_load_dwordx2 v[106:107], v[152:153], off offset:416
	global_load_dwordx2 v[108:109], v[152:153], off offset:448
	global_load_dwordx2 v[110:111], v[152:153], off offset:480
	global_load_dword v142, v[2:3], off
	global_load_dword v143, v[2:3], off offset:12
	global_load_dword v144, v[2:3], off offset:24
	global_load_dword v145, v[2:3], off offset:36
	s_andn2_b64 vcc, exec, s[14:15]
	s_cbranch_vccnz .Lnsa_epi_nog
	global_load_dwordx2 v[112:113], v[164:165], off
	global_load_dwordx2 v[114:115], v[164:165], off offset:32
	global_load_dwordx2 v[116:117], v[164:165], off offset:64
	global_load_dwordx2 v[118:119], v[164:165], off offset:96
	global_load_dwordx2 v[120:121], v[164:165], off offset:128
	global_load_dwordx2 v[122:123], v[164:165], off offset:160
	global_load_dwordx2 v[124:125], v[164:165], off offset:192
	global_load_dwordx2 v[126:127], v[164:165], off offset:224
	global_load_dwordx2 v[128:129], v[164:165], off offset:256
	global_load_dwordx2 v[130:131], v[164:165], off offset:288
	global_load_dwordx2 v[132:133], v[164:165], off offset:320
	global_load_dwordx2 v[134:135], v[164:165], off offset:352
	global_load_dwordx2 v[136:137], v[164:165], off offset:384
	global_load_dwordx2 v[138:139], v[164:165], off offset:416
	global_load_dwordx2 v[140:141], v[164:165], off offset:448
	global_load_dwordx2 v[146:147], v[164:165], off offset:480
